# 16 late W_in panels (pn 11..26) on side CUs (poll at round 3) + batched LDS read-back in the side CUs' transposing item body
# speedup vs baseline: 1.0115x; 1.0020x over previous
; #define LAS __attribute__((address_space(3)))
; __device__ __forceinline__ int win_src_col(int np) { const int t = np >> 8, i = np & 255; return (t >= 12 && t < 24) ? ((i < 128) ? 3072 + 128 * (t - 12) + i : 4608 + 128 * (t - 12) + (i - 128)) : np; }
; __device__ __forceinline__ void p0_items(Frame& F, int first, int last, int gw, int NGW) {
;     LAS float* scr = (LAS float*)(F.lds + F.wave * 16640);
;     bf16_t* WIN = WSP(bf16_t, WS_WIN); bf16_t* WKV = WSP(bf16_t, WS_WKV); bf16_t* WOUT = WSP(bf16_t, WS_WOUT); bf16_t* WPW = WSP(bf16_t, WS_WPW); bf16_t* WPOOL = WSP(bf16_t, WS_WPOOL);
;     for (int it = first + gw; it < last; it += NGW) {
;         int r = it; const float* src; bf16_t* dst; int ldw, ldt;
;         if (r < I_IN) { const int kb = r / 152, nb = r % 152; src = F.in[9] + (size_t)(64 * kb) * DIN + win_src_col(64 * nb); ldw = DIN; dst = WIN + (size_t)(64 * nb) * DM + 64 * kb; ldt = DM; }
; __device__ __forceinline__ void p0_prologue(Frame& F, bool all_weights) {
;     const int gw = F.vcu * NWAVES + F.wave, NGW = F.G * NWAVES;
;     p0_items(F, 0, all_weights ? NITEMS : NITEMS_EARLY, gw, NGW);
.LBB0_7:
	s_mov_b64 s[48:49], s[0:1]
	s_ashr_i32 s13, s4, 6
	s_load_dwordx4 s[16:19], s[48:49], 0x0
	s_load_dwordx2 s[44:45], s[48:49], 0x10
	s_load_dwordx8 s[4:11], s[48:49], 0x38
	s_load_dwordx4 s[20:23], s[48:49], 0x58
	s_load_dwordx2 s[42:43], s[48:49], 0xb0
	s_cmpk_lg_i32 s3, 0x100
	s_cselect_b64 s[46:47], -1, 0
	s_lshl_b32 s24, s12, 3
	s_add_i32 s40, s24, s13
	s_lshl_b32 s28, s3, 3
	s_cmpk_eq_i32 s3, 0x100
	s_cselect_b64 s[38:39], -1, 0
	s_movk_i32 s26, 0x1600
	s_and_b64 s[24:25], s[38:39], exec
	v_and_b32_e32 v1, 63, v7
	s_cselect_b32 s29, s26, 0x40d0
	s_cmp_ge_i32 s40, s29
	v_lshlrev_b32_e32 v6, 3, v1
	s_cbranch_scc1 .LBB0_35
	s_waitcnt lgkmcnt(0)
	s_add_u32 s34, s42, 0x20e00000
	s_addc_u32 s35, s43, 0
	s_add_u32 s36, s42, 0x1fe00000
	s_addc_u32 s37, s43, 0
	s_add_u32 s41, s42, 0x100000
	s_addc_u32 s60, s43, 0
	s_add_u32 s61, s42, 0x2100000
	s_addc_u32 s62, s43, 0
	s_load_dwordx4 s[24:27], s[48:49], 0x90
	s_add_u32 s63, s42, 0x2600000
	s_mul_i32 s48, s13, 0x4100
	s_addc_u32 s64, s43, 0
	s_add_i32 s48, s48, 0
	v_lshrrev_b32_e32 v10, 4, v1
	v_and_b32_e32 v4, 15, v7
	v_lshl_add_u32 v9, v4, 4, s48
	v_mul_u32_u24_e32 v35, 0x104, v10
	v_lshrrev_b32_e32 v26, 3, v1
	v_and_b32_e32 v8, 56, v6
	v_lshlrev_b32_e32 v2, 2, v4
	v_mov_b32_e32 v3, 0
	v_mul_u32_u24_e32 v4, 0x104, v8
	v_lshlrev_b32_e32 v5, 2, v26
	v_add_u32_e32 v35, v9, v35
	s_mov_b32 s49, 0
	v_or_b32_e32 v11, 4, v10
	v_or_b32_e32 v12, 8, v10
	v_or_b32_e32 v13, 12, v10
	v_or_b32_e32 v14, 16, v10
	v_or_b32_e32 v15, 20, v10
	v_or_b32_e32 v16, 24, v10
	v_or_b32_e32 v17, 28, v10
	v_or_b32_e32 v18, 32, v10
	v_or_b32_e32 v19, 36, v10
	v_or_b32_e32 v20, 40, v10
	v_or_b32_e32 v21, 44, v10
	v_or_b32_e32 v22, 48, v10
	v_or_b32_e32 v23, 52, v10
	v_or_b32_e32 v24, 56, v10
	v_or_b32_e32 v25, 60, v10
	v_add3_u32 v27, s48, v4, v5
	v_or_b32_e32 v28, 8, v26
	v_or_b32_e32 v29, 16, v26
	v_or_b32_e32 v30, 24, v26
	v_or_b32_e32 v31, 32, v26
	v_or_b32_e32 v32, 40, v26
	v_or_b32_e32 v33, 48, v26
	v_or_b32_e32 v34, 56, v26
	s_lshl_b32 s65, s40, 6
	s_lshl_b32 s66, s3, 9
	s_lshl_b32 s67, s40, 2
	s_lshl_b32 s68, s3, 5
	v_lshlrev_b32_e32 v4, 2, v2
	v_mov_b32_e32 v5, v3
	v_add_u32_e32 v36, 0x410, v35
	v_add_u32_e32 v37, 0x418, v35
	v_add_u32_e32 v38, 0x820, v35
	v_add_u32_e32 v39, 0x828, v35
	v_add_u32_e32 v40, 0xc30, v35
	v_add_u32_e32 v41, 0xc38, v35
	v_add_u32_e32 v42, 0x1040, v35
	v_add_u32_e32 v43, 0x1048, v35
	v_add_u32_e32 v44, 0x1450, v35
	v_add_u32_e32 v45, 0x1458, v35
	v_add_u32_e32 v46, 0x1860, v35
	v_add_u32_e32 v47, 0x1868, v35
	v_add_u32_e32 v48, 0x1c70, v35
	v_add_u32_e32 v49, 0x1c78, v35
	v_add_u32_e32 v50, 0x2080, v35
	v_add_u32_e32 v51, 0x2088, v35
	v_add_u32_e32 v52, 0x2490, v35
	v_add_u32_e32 v53, 0x2498, v35
	v_add_u32_e32 v54, 0x28a0, v35
	v_add_u32_e32 v55, 0x28a8, v35
	v_add_u32_e32 v56, 0x2cb0, v35
	v_add_u32_e32 v57, 0x2cb8, v35
	v_add_u32_e32 v58, 0x30c0, v35
	v_add_u32_e32 v59, 0x30c8, v35
	v_lshlrev_b32_e32 v8, 1, v8
	v_mov_b32_e32 v9, v3
	s_mov_b32 s69, s40
	v_add_u32_e32 v60, 0x34d0, v35
	v_add_u32_e32 v61, 0x34d8, v35
	v_add_u32_e32 v62, 0x38e0, v35
	v_add_u32_e32 v63, 0x38e8, v35
	s_branch .LBB0_11

; #define LAS __attribute__((address_space(3)))
; __device__ __forceinline__ int win_src_col(int np) { const int t = np >> 8, i = np & 255; return (t >= 12 && t < 24) ? ((i < 128) ? 3072 + 128 * (t - 12) + i : 4608 + 128 * (t - 12) + (i - 128)) : np; }
; __device__ __forceinline__ void p0_items(Frame& F, int first, int last, int gw, int NGW) {
;     LAS float* scr = (LAS float*)(F.lds + F.wave * 16640);
;     bf16_t* WIN = WSP(bf16_t, WS_WIN); bf16_t* WKV = WSP(bf16_t, WS_WKV); bf16_t* WOUT = WSP(bf16_t, WS_WOUT); bf16_t* WPW = WSP(bf16_t, WS_WPW); bf16_t* WPOOL = WSP(bf16_t, WS_WPOOL);
;     for (int it = first + gw; it < last; it += NGW) {
;         int r = it; const float* src; bf16_t* dst; int ldw, ldt;
;         if (r < I_IN) { const int kb = r / 152, nb = r % 152; src = F.in[9] + (size_t)(64 * kb) * DIN + win_src_col(64 * nb); ldw = DIN; dst = WIN + (size_t)(64 * nb) * DM + 64 * kb; ldt = DM; }
.LBB0_29:
	s_andn2_b64 vcc, exec, s[58:59]
	s_cbranch_vccnz .LBB0_10
	s_mul_hi_u32 s48, s69, 0x2e8ba2f
	s_lshr_b32 s48, s48, 0
	s_mul_i32 s50, s48, 0x58
	s_sub_i32 s51, s69, s50
	s_cmp_gt_u32 s51, 43
	s_cselect_b32 s50, 64, 0
	s_add_i32 s51, s51, s50
	s_ashr_i32 s53, s51, 2
	s_lshl_b32 s50, s51, 6
	s_add_i32 s51, s53, -12
	s_cmp_gt_u32 s51, 11
	s_mov_b32 s52, s50
	s_cbranch_scc1 .LBB0_9
	s_and_b32 s51, s50, 0xc0
	s_lshl_b32 s53, s53, 7
	s_cmpk_gt_u32 s51, 0x7f
	s_mov_b64 s[54:55], -1
	s_cbranch_scc0 .LBB0_33
	s_add_i32 s52, s51, s53
	s_addk_i32 s52, 0xb80
	s_mov_b64 s[54:55], 0

; template <class Epi, class Sched, bool ALIGN_EPI, bool SP2, bool BPRE = false>
; __device__ __forceinline__ void gemm_phase(LAS unsigned char* lds, const int pitchA, const int pitchB, const Sched& S, const Epi& E) {
;     ...
;     for (;;) {
;         const bool has_next = S.next(ui + 1, nxt);
;         const char* nA = has_next ? nxt.A : cA; const char* nB = has_next ? nxt.B : cB;
;     ...
;         cur = nxt; cA = nA; cB = nB; ++ui;
.LBB0_136:
	s_add_i32 s12, s12, 1
	s_cmp_lg_u32 s12, 3
	s_cbranch_scc1 .Lw_ready
	s_mov_b32 s99, 0

; #define LAS __attribute__((address_space(3)))
; __device__ __forceinline__ int win_src_col(int np) { const int t = np >> 8, i = np & 255; return (t >= 12 && t < 24) ? ((i < 128) ? 3072 + 128 * (t - 12) + i : 4608 + 128 * (t - 12) + (i - 128)) : np; }
; __device__ __forceinline__ void p0_items(Frame& F, int first, int last, int gw, int NGW) {
;     LAS float* scr = (LAS float*)(F.lds + F.wave * 16640);
;     bf16_t* WIN = WSP(bf16_t, WS_WIN); bf16_t* WKV = WSP(bf16_t, WS_WKV); bf16_t* WOUT = WSP(bf16_t, WS_WOUT); bf16_t* WPW = WSP(bf16_t, WS_WPW); bf16_t* WPOOL = WSP(bf16_t, WS_WPOOL);
;     for (int it = first + gw; it < last; it += NGW) {
;         int r = it; const float* src; bf16_t* dst; int ldw, ldt;
;         if (r < I_IN) { const int kb = r / 152, nb = r % 152; src = F.in[9] + (size_t)(64 * kb) * DIN + win_src_col(64 * nb); ldw = DIN; dst = WIN + (size_t)(64 * nb) * DM + 64 * kb; ldt = DM; }
; __global__ void __launch_bounds__(NTHR, 2) hybrid_fwd(Args args) {
;     ...
;     {
;         constexpr int NFREE = 256 - NAS_FREE_FROM, N3 = NAS_UNITS - 2 * NFREE, NLATE = NFREE - N3;
;         const int idx = (int)blockIdx.x - NAS_FREE_FROM - N3;
;         if (idx >= 0 && (int)gridDim.x == 256) { Frame F = make_frame(lds);
;             p0_items(F, NITEMS_EARLY, NITEMS, idx * NWAVES + F.wave, NLATE * NWAVES);
;             p0_pool_pad(F, idx * NTHR + F.tid, NLATE * NTHR); p0_pool_frag(F, idx * NTHR + F.tid, NLATE * NTHR); }
.Lnot_p3:
	s_bitcmp1_b32 s98, 1
	s_cbranch_scc1 .Lside_done
	s_cmpk_lt_i32 s2, 0xe0
	s_cselect_b64 s[6:7], -1, 0
	s_xor_b64 s[8:9], s[38:39], -1
	s_or_b64 s[6:7], s[6:7], s[8:9]
	s_and_b64 vcc, exec, s[6:7]
	s_cbranch_vccnz .LBB0_347
	v_mov_b32_e32 v1, v0
	s_mov_b64 s[38:39], s[0:1]
	s_add_i32 s12, s2, 0xffffff20
	v_readfirstlane_b32 s6, v1
	s_ashr_i32 s40, s6, 6
	s_load_dwordx8 s[16:23], s[38:39], 0x48
	s_load_dwordx2 s[6:7], s[38:39], 0xb0
	s_lshl_b32 s8, s12, 3
	s_add_i32 s41, s40, s8
	s_cmpk_gt_i32 s41, 0x12cf
	v_and_b32_e32 v6, 15, v1
	s_cbranch_scc1 .LBB0_340
	s_waitcnt lgkmcnt(0)
	s_add_u32 s13, s6, 0x20e00000
	s_addc_u32 s29, s7, 0
	s_add_u32 s34, s6, 0x1fe00000
	s_addc_u32 s35, s7, 0
	s_add_u32 s36, s6, 0x100000
	s_addc_u32 s37, s7, 0
	s_add_u32 s50, s6, 0x2100000
	s_addc_u32 s51, s7, 0
	s_load_dwordx4 s[8:11], s[38:39], 0x90
	s_add_u32 s52, s6, 0x2600000
	s_mulk_i32 s40, 0x4100
	s_addc_u32 s53, s7, 0
	s_add_i32 s38, s40, 0
	v_bfe_u32 v7, v1, 4, 2
	v_lshlrev_b32_e32 v4, 3, v1
	v_lshl_add_u32 v9, v6, 4, s38
	v_mul_u32_u24_e32 v34, 0x104, v7
	v_bfe_u32 v25, v1, 3, 3
	v_and_b32_e32 v8, 56, v4
	s_add_i32 s54, s41, 0x1600
	v_lshlrev_b32_e32 v2, 2, v6
	v_mov_b32_e32 v3, 0
	v_mul_u32_u24_e32 v4, 0x104, v8
	v_lshlrev_b32_e32 v5, 2, v25
	v_add_u32_e32 v34, v9, v34
	s_mov_b32 s39, 0
	v_or_b32_e32 v10, 4, v7
	v_or_b32_e32 v11, 8, v7
	v_or_b32_e32 v12, 12, v7
	v_or_b32_e32 v13, 16, v7
	v_or_b32_e32 v14, 20, v7
	v_or_b32_e32 v15, 24, v7
	v_or_b32_e32 v16, 28, v7
	v_or_b32_e32 v17, 32, v7
	v_or_b32_e32 v18, 36, v7
	v_or_b32_e32 v19, 40, v7
	v_or_b32_e32 v20, 44, v7
	v_or_b32_e32 v21, 48, v7
	v_or_b32_e32 v22, 52, v7
	v_or_b32_e32 v23, 56, v7
	v_or_b32_e32 v24, 60, v7
	v_add3_u32 v26, s38, v4, v5
	v_or_b32_e32 v27, 8, v25
	v_or_b32_e32 v28, 16, v25
	v_or_b32_e32 v29, 24, v25
	v_or_b32_e32 v30, 32, v25
	v_or_b32_e32 v31, 40, v25
	v_or_b32_e32 v32, 48, v25
	v_or_b32_e32 v33, 56, v25
	s_lshl_b32 s55, s54, 6
	s_lshl_b32 s56, s54, 2
	v_lshlrev_b32_e32 v4, 2, v2
	v_mov_b32_e32 v5, v3
	v_add_u32_e32 v35, 0x410, v34
	v_add_u32_e32 v36, 0x418, v34
	v_add_u32_e32 v37, 0x820, v34
	v_add_u32_e32 v38, 0x828, v34
	v_add_u32_e32 v39, 0xc30, v34
	v_add_u32_e32 v40, 0xc38, v34
	v_add_u32_e32 v41, 0x1040, v34
	v_add_u32_e32 v42, 0x1048, v34
	v_add_u32_e32 v43, 0x1450, v34
	v_add_u32_e32 v44, 0x1458, v34
	v_add_u32_e32 v45, 0x1860, v34
	v_add_u32_e32 v46, 0x1868, v34
	v_add_u32_e32 v47, 0x1c70, v34
	v_add_u32_e32 v48, 0x1c78, v34
	v_add_u32_e32 v49, 0x2080, v34
	v_add_u32_e32 v50, 0x2088, v34
	v_add_u32_e32 v51, 0x2490, v34
	v_add_u32_e32 v52, 0x2498, v34
	v_add_u32_e32 v53, 0x28a0, v34
	v_add_u32_e32 v54, 0x28a8, v34
	v_add_u32_e32 v55, 0x2cb0, v34
	v_add_u32_e32 v56, 0x2cb8, v34
	v_add_u32_e32 v57, 0x30c0, v34
	v_add_u32_e32 v58, 0x30c8, v34
	v_add_u32_e32 v59, 0x34d0, v34
	v_lshlrev_b32_e32 v8, 1, v8
	v_mov_b32_e32 v9, v3
	v_add_u32_e32 v60, 0x34d8, v34
	v_add_u32_e32 v61, 0x38e0, v34
	s_branch .LBB0_316

; #define LAS __attribute__((address_space(3)))
; #define GAS __attribute__((address_space(1)))
; #define LDS_WAIT() asm volatile("s_waitcnt lgkmcnt(0)" ::: "memory")
; __device__ __forceinline__ void p0_transpose_item(const float* Wsrc  , int ldw, bf16_t* dst  , int ldt, LAS float* scr, int lane) {
;     const int r = lane >> 4, c4 = lane & 15;
;     f32x4 v[16];
; #pragma unroll
;     for (int i = 0; i < 16; ++i) v[i] = __builtin_nontemporal_load((const GAS f32x4*)(Wsrc + (size_t)(4 * i + r) * ldw + 4 * c4));
; #pragma unroll
;     for (int i = 0; i < 16; ++i) { LAS float* s = scr + (4 * i + r) * 65 + 4 * c4; s[0] = v[i].x; s[1] = v[i].y; s[2] = v[i].z; s[3] = v[i].w; }
;     LDS_WAIT(); asm volatile("" ::: "memory");
.LBB0_315:
	v_mul_u32_u24_e32 v2, s46, v7
	v_lshl_add_u64 v[122:123], s[44:45], 0, v[4:5]
	v_lshlrev_b32_e32 v2, 2, v2
	v_lshl_add_u64 v[62:63], v[122:123], 0, v[2:3]
	v_mul_u32_u24_e32 v2, s46, v10
	v_lshlrev_b32_e32 v2, 2, v2
	v_lshl_add_u64 v[66:67], v[122:123], 0, v[2:3]
	v_mul_u32_u24_e32 v2, s46, v11
	v_lshlrev_b32_e32 v2, 2, v2
	v_lshl_add_u64 v[70:71], v[122:123], 0, v[2:3]
	v_mul_u32_u24_e32 v2, s46, v12
	v_lshlrev_b32_e32 v2, 2, v2
	v_lshl_add_u64 v[74:75], v[122:123], 0, v[2:3]
	v_mul_u32_u24_e32 v2, s46, v13
	v_lshlrev_b32_e32 v2, 2, v2
	v_lshl_add_u64 v[78:79], v[122:123], 0, v[2:3]
	v_mul_u32_u24_e32 v2, s46, v14
	v_lshlrev_b32_e32 v2, 2, v2
	v_lshl_add_u64 v[82:83], v[122:123], 0, v[2:3]
	v_mul_u32_u24_e32 v2, s46, v15
	v_lshlrev_b32_e32 v2, 2, v2
	v_lshl_add_u64 v[86:87], v[122:123], 0, v[2:3]
	v_mul_u32_u24_e32 v2, s46, v16
	v_lshlrev_b32_e32 v2, 2, v2
	v_lshl_add_u64 v[90:91], v[122:123], 0, v[2:3]
	v_mul_u32_u24_e32 v2, s46, v17
	v_lshlrev_b32_e32 v2, 2, v2
	v_lshl_add_u64 v[94:95], v[122:123], 0, v[2:3]
	v_mul_u32_u24_e32 v2, s46, v18
	v_lshlrev_b32_e32 v2, 2, v2
	v_lshl_add_u64 v[98:99], v[122:123], 0, v[2:3]
	v_mul_u32_u24_e32 v2, s46, v19
	v_lshlrev_b32_e32 v2, 2, v2
	v_lshl_add_u64 v[102:103], v[122:123], 0, v[2:3]
	v_mul_u32_u24_e32 v2, s46, v20
	v_lshlrev_b32_e32 v2, 2, v2
	v_lshl_add_u64 v[106:107], v[122:123], 0, v[2:3]
	v_mul_u32_u24_e32 v2, s46, v21
	v_lshlrev_b32_e32 v2, 2, v2
	v_lshl_add_u64 v[110:111], v[122:123], 0, v[2:3]
	v_mul_u32_u24_e32 v2, s46, v22
	v_lshlrev_b32_e32 v2, 2, v2
	v_lshl_add_u64 v[114:115], v[122:123], 0, v[2:3]
	global_load_dwordx4 v[62:65], v[62:63], off nt
	s_nop 0
	global_load_dwordx4 v[66:69], v[66:67], off nt
	s_nop 0
	global_load_dwordx4 v[70:73], v[70:71], off nt
	s_nop 0
	global_load_dwordx4 v[74:77], v[74:75], off nt
	s_nop 0
	global_load_dwordx4 v[78:81], v[78:79], off nt
	s_nop 0
	global_load_dwordx4 v[82:85], v[82:83], off nt
	s_nop 0
	global_load_dwordx4 v[86:89], v[86:87], off nt
	s_nop 0
	global_load_dwordx4 v[90:93], v[90:91], off nt
	s_nop 0
	global_load_dwordx4 v[94:97], v[94:95], off nt
	s_nop 0
	global_load_dwordx4 v[98:101], v[98:99], off nt
	s_nop 0
	global_load_dwordx4 v[102:105], v[102:103], off nt
	s_nop 0
	global_load_dwordx4 v[106:109], v[106:107], off nt
	s_nop 0
	global_load_dwordx4 v[110:113], v[110:111], off nt
	s_nop 0
	global_load_dwordx4 v[114:117], v[114:115], off nt
	v_mul_u32_u24_e32 v2, s46, v23
	v_lshlrev_b32_e32 v2, 2, v2
	v_lshl_add_u64 v[118:119], v[122:123], 0, v[2:3]
	v_mul_u32_u24_e32 v2, s46, v24
	global_load_dwordx4 v[118:121], v[118:119], off nt
	v_lshlrev_b32_e32 v2, 2, v2
	v_lshl_add_u64 v[122:123], v[122:123], 0, v[2:3]
	global_load_dwordx4 v[122:125], v[122:123], off nt
	v_add_u32_e32 v2, 0x38e8, v34
	v_add_u32_e32 v126, 0x3cf0, v34
	v_add_u32_e32 v127, 0x3cf8, v34
	s_add_i32 s38, s54, 0x100
	s_add_i32 s55, s55, 0x4000
	s_addk_i32 s56, 0x400
	s_cmpk_lt_i32 s54, 0x3fd0
	s_mov_b32 s54, s38
	s_waitcnt vmcnt(0)
	ds_write2_b32 v34, v62, v63 offset1:1
	ds_write2_b32 v34, v64, v65 offset0:2 offset1:3
	ds_write2_b32 v35, v66, v67 offset1:1
	ds_write2_b32 v36, v68, v69 offset1:1
	ds_write2_b32 v37, v70, v71 offset1:1
	ds_write2_b32 v38, v72, v73 offset1:1
	ds_write2_b32 v39, v74, v75 offset1:1
	ds_write2_b32 v40, v76, v77 offset1:1
	ds_write2_b32 v41, v78, v79 offset1:1
	ds_write2_b32 v42, v80, v81 offset1:1
	ds_write2_b32 v43, v82, v83 offset1:1
	ds_write2_b32 v44, v84, v85 offset1:1
	ds_write2_b32 v45, v86, v87 offset1:1
	ds_write2_b32 v46, v88, v89 offset1:1
	ds_write2_b32 v47, v90, v91 offset1:1
	ds_write2_b32 v48, v92, v93 offset1:1
	ds_write2_b32 v49, v94, v95 offset1:1
	ds_write2_b32 v50, v96, v97 offset1:1
	ds_write2_b32 v51, v98, v99 offset1:1
	ds_write2_b32 v52, v100, v101 offset1:1
	ds_write2_b32 v53, v102, v103 offset1:1
	ds_write2_b32 v54, v104, v105 offset1:1
	ds_write2_b32 v55, v106, v107 offset1:1
	ds_write2_b32 v56, v108, v109 offset1:1
	ds_write2_b32 v57, v110, v111 offset1:1
	ds_write2_b32 v58, v112, v113 offset1:1
	ds_write2_b32 v59, v114, v115 offset1:1
	ds_write2_b32 v60, v116, v117 offset1:1
	ds_write2_b32 v61, v118, v119 offset1:1
	ds_write2_b32 v2, v120, v121 offset1:1
	ds_write2_b32 v126, v122, v123 offset1:1
	ds_write2_b32 v127, v124, v125 offset1:1
	s_waitcnt lgkmcnt(0)
; #define LAS __attribute__((address_space(3)))
; #define GAS __attribute__((address_space(1)))
; #define LDS_WAIT() asm volatile("s_waitcnt lgkmcnt(0)" ::: "memory")
; __device__ __forceinline__ unsigned cvt_pk_bf16(float lo, float hi) { unsigned r; asm volatile("v_cvt_pk_bf16_f32 %0, %1, %2" : "=v"(r) : "v"(lo), "v"(hi)); return r; }
; __device__ __forceinline__ void p0_transpose_item(const float* Wsrc  , int ldw, bf16_t* dst  , int ldt, LAS float* scr, int lane) {
;     ...
;     LDS_WAIT(); asm volatile("" ::: "memory");
;     const int c = lane & 7;
; #pragma unroll
;     for (int j = 0; j < 8; ++j) { const int n = (lane >> 3) + 8 * j; const LAS float* s = scr + (8 * c) * 65 + n;
;         u32x4 o; o.x = cvt_pk_bf16(s[0 * 65], s[1 * 65]); o.y = cvt_pk_bf16(s[2 * 65], s[3 * 65]); o.z = cvt_pk_bf16(s[4 * 65], s[5 * 65]); o.w = cvt_pk_bf16(s[6 * 65], s[7 * 65]);
;         *(GAS u32x4*)(dst + (size_t)n * ldt + 8 * c) = o; }
;     LDS_WAIT(); asm volatile("" ::: "memory");
	v_add_u32_e32 v72, 0x400, v26
	ds_read2_b32 v[128:129], v26 offset1:65
	ds_read2_b32 v[130:131], v26 offset0:130 offset1:195
	ds_read2_b32 v[132:133], v72 offset0:4 offset1:69
	ds_read2_b32 v[134:135], v72 offset0:134 offset1:199
	ds_read2_b32 v[136:137], v26 offset0:8 offset1:73
	ds_read2_b32 v[138:139], v26 offset0:138 offset1:203
	ds_read2_b32 v[140:141], v72 offset0:12 offset1:77
	ds_read2_b32 v[142:143], v72 offset0:142 offset1:207
	s_waitcnt lgkmcnt(0)
	v_cvt_pk_bf16_f32 v192, v128, v129
	v_cvt_pk_bf16_f32 v193, v130, v131
	v_cvt_pk_bf16_f32 v194, v132, v133
	v_cvt_pk_bf16_f32 v195, v134, v135
	v_cvt_pk_bf16_f32 v196, v136, v137
	v_cvt_pk_bf16_f32 v197, v138, v139
	v_cvt_pk_bf16_f32 v198, v140, v141
	v_cvt_pk_bf16_f32 v199, v142, v143
	v_mul_u32_u24_e32 v2, s40, v25
	v_lshl_add_u64 v[68:69], s[42:43], 0, v[8:9]
	v_lshlrev_b32_e32 v2, 1, v2
	v_lshl_add_u64 v[70:71], v[68:69], 0, v[2:3]
	global_store_dwordx4 v[70:71], v[192:195], off
	v_mul_u32_u24_e32 v2, s40, v27
	v_lshlrev_b32_e32 v2, 1, v2
	v_lshl_add_u64 v[70:71], v[68:69], 0, v[2:3]
	global_store_dwordx4 v[70:71], v[196:199], off
	ds_read2_b32 v[144:145], v26 offset0:16 offset1:81
	ds_read2_b32 v[146:147], v26 offset0:146 offset1:211
	ds_read2_b32 v[148:149], v72 offset0:20 offset1:85
	ds_read2_b32 v[150:151], v72 offset0:150 offset1:215
	ds_read2_b32 v[152:153], v26 offset0:24 offset1:89
	ds_read2_b32 v[154:155], v26 offset0:154 offset1:219
	ds_read2_b32 v[156:157], v72 offset0:28 offset1:93
	ds_read2_b32 v[158:159], v72 offset0:158 offset1:223
	s_waitcnt lgkmcnt(0)
	v_cvt_pk_bf16_f32 v200, v144, v145
	v_cvt_pk_bf16_f32 v201, v146, v147
	v_cvt_pk_bf16_f32 v202, v148, v149
	v_cvt_pk_bf16_f32 v203, v150, v151
	v_cvt_pk_bf16_f32 v204, v152, v153
	v_cvt_pk_bf16_f32 v205, v154, v155
	v_cvt_pk_bf16_f32 v206, v156, v157
	v_cvt_pk_bf16_f32 v207, v158, v159
	v_mul_u32_u24_e32 v2, s40, v28
	v_lshlrev_b32_e32 v2, 1, v2
	v_lshl_add_u64 v[70:71], v[68:69], 0, v[2:3]
	global_store_dwordx4 v[70:71], v[200:203], off
	v_mul_u32_u24_e32 v2, s40, v29
	v_lshlrev_b32_e32 v2, 1, v2
	v_lshl_add_u64 v[70:71], v[68:69], 0, v[2:3]
	global_store_dwordx4 v[70:71], v[204:207], off
	ds_read2_b32 v[160:161], v26 offset0:32 offset1:97
	ds_read2_b32 v[162:163], v26 offset0:162 offset1:227
	ds_read2_b32 v[164:165], v72 offset0:36 offset1:101
	ds_read2_b32 v[166:167], v72 offset0:166 offset1:231
	ds_read2_b32 v[168:169], v26 offset0:40 offset1:105
	ds_read2_b32 v[170:171], v26 offset0:170 offset1:235
	ds_read2_b32 v[172:173], v72 offset0:44 offset1:109
	ds_read2_b32 v[174:175], v72 offset0:174 offset1:239
	s_waitcnt lgkmcnt(0)
	v_cvt_pk_bf16_f32 v208, v160, v161
	v_cvt_pk_bf16_f32 v209, v162, v163
	v_cvt_pk_bf16_f32 v210, v164, v165
	v_cvt_pk_bf16_f32 v211, v166, v167
	v_cvt_pk_bf16_f32 v212, v168, v169
	v_cvt_pk_bf16_f32 v213, v170, v171
	v_cvt_pk_bf16_f32 v214, v172, v173
	v_cvt_pk_bf16_f32 v215, v174, v175
	v_mul_u32_u24_e32 v2, s40, v30
	v_lshlrev_b32_e32 v2, 1, v2
	v_lshl_add_u64 v[70:71], v[68:69], 0, v[2:3]
	global_store_dwordx4 v[70:71], v[208:211], off
	v_mul_u32_u24_e32 v2, s40, v31
	v_lshlrev_b32_e32 v2, 1, v2
	v_lshl_add_u64 v[70:71], v[68:69], 0, v[2:3]
	global_store_dwordx4 v[70:71], v[212:215], off
	ds_read2_b32 v[176:177], v26 offset0:48 offset1:113
	ds_read2_b32 v[178:179], v26 offset0:178 offset1:243
	ds_read2_b32 v[180:181], v72 offset0:52 offset1:117
	ds_read2_b32 v[182:183], v72 offset0:182 offset1:247
	ds_read2_b32 v[184:185], v26 offset0:56 offset1:121
	ds_read2_b32 v[186:187], v26 offset0:186 offset1:251
	ds_read2_b32 v[188:189], v72 offset0:60 offset1:125
	ds_read2_b32 v[190:191], v72 offset0:190 offset1:255
	s_waitcnt lgkmcnt(0)
	v_cvt_pk_bf16_f32 v216, v176, v177
	v_cvt_pk_bf16_f32 v217, v178, v179
	v_cvt_pk_bf16_f32 v218, v180, v181
	v_cvt_pk_bf16_f32 v219, v182, v183
	v_cvt_pk_bf16_f32 v220, v184, v185
	v_cvt_pk_bf16_f32 v221, v186, v187
	v_cvt_pk_bf16_f32 v222, v188, v189
	v_cvt_pk_bf16_f32 v223, v190, v191
	v_mul_u32_u24_e32 v2, s40, v32
	v_lshlrev_b32_e32 v2, 1, v2
	v_lshl_add_u64 v[70:71], v[68:69], 0, v[2:3]
	v_mul_u32_u24_e32 v2, s40, v33
	global_store_dwordx4 v[70:71], v[216:219], off
	v_lshlrev_b32_e32 v2, 1, v2
	v_lshl_add_u64 v[68:69], v[68:69], 0, v[2:3]
	global_store_dwordx4 v[68:69], v[220:223], off
	s_cbranch_scc0 .LBB0_340

; #define LAS __attribute__((address_space(3)))
; __device__ __forceinline__ int win_src_col(int np) { const int t = np >> 8, i = np & 255; return (t >= 12 && t < 24) ? ((i < 128) ? 3072 + 128 * (t - 12) + i : 4608 + 128 * (t - 12) + (i - 128)) : np; }
; __device__ __forceinline__ void p0_items(Frame& F, int first, int last, int gw, int NGW) {
;     LAS float* scr = (LAS float*)(F.lds + F.wave * 16640);
;     bf16_t* WIN = WSP(bf16_t, WS_WIN); bf16_t* WKV = WSP(bf16_t, WS_WKV); bf16_t* WOUT = WSP(bf16_t, WS_WOUT); bf16_t* WPW = WSP(bf16_t, WS_WPW); bf16_t* WPOOL = WSP(bf16_t, WS_WPOOL);
;     for (int it = first + gw; it < last; it += NGW) {
;         int r = it; const float* src; bf16_t* dst; int ldw, ldt;
;         if (r < I_IN) { const int kb = r / 152, nb = r % 152; src = F.in[9] + (size_t)(64 * kb) * DIN + win_src_col(64 * nb); ldw = DIN; dst = WIN + (size_t)(64 * nb) * DM + 64 * kb; ldt = DM; }
;         else if ((r -= I_IN) < I_KV) { const int kb = r / 16, nb = r % 16; src = F.in[10] + (size_t)(64 * kb) * DX + 64 * nb; ldw = DX; dst = WKV + (size_t)(64 * nb) * DM + 64 * kb; ldt = DM; }
.LBB0_334:
	s_andn2_b64 vcc, exec, s[48:49]
	s_cbranch_vccnz .LBB0_315
	s_sub_i32 s41, s54, 0x1600
	s_mul_hi_u32 s38, s41, 0x4000000
	s_lshr_b32 s38, s38, 0
	s_mul_i32 s40, s38, 64
	s_sub_i32 s41, s41, s40
	s_add_i32 s41, s41, 44
	s_ashr_i32 s43, s41, 2
	s_lshl_b32 s40, s41, 6
	s_nop 0
	s_add_i32 s41, s43, -12
	s_cmp_gt_u32 s41, 11
	s_mov_b32 s42, s40
	s_cbranch_scc1 .LBB0_314
	s_and_b32 s41, s40, 0xc0
	s_lshl_b32 s43, s43, 7
	s_cmpk_gt_u32 s41, 0x7f
	s_mov_b64 s[44:45], -1
	s_cbranch_scc0 .LBB0_338
	s_add_i32 s42, s41, s43
	s_addk_i32 s42, 0xb80
	s_mov_b64 s[44:45], 0
